# k19 + S3: loop-top vmcnt(0) hoisted out of the scan loop so each iteration's loads overlap the previous iteration's store acks
# speedup vs baseline: 1.0108x; 1.0077x over previous
.LBB0_1474:
	s_lshl_b32 s4, s17, 12
	s_lshl_b32 s8, s13, 1
	s_and_b32 s4, s4, 0x7c000
	s_and_b32 s8, s8, 0x3000
	s_or_b32 s4, s4, s8
	s_ashr_i32 s18, s17, 7
	v_readlane_b32 s20, v254, 0
	s_cmpk_lt_u32 s17, 0x80
	v_readlane_b32 s21, v254, 1
	v_readlane_b32 s22, v254, 2
	v_readlane_b32 s23, v254, 3
	s_cselect_b32 s21, s23, s1
	s_cselect_b32 s20, s22, s0
	s_ashr_i32 s19, s18, 31
	s_lshl_b64 s[18:19], s[18:19], 13
	s_add_u32 s8, s9, s18
	s_addc_u32 s10, s11, s19
	s_and_b32 s12, s17, 0x7c
	s_add_u32 s18, s8, s12
	s_addc_u32 s19, s10, 0
	global_load_dword v11, v10, s[18:19] sc1
	v_lshl_add_u64 v[4:5], s[20:21], 0, v[2:3]
	v_lshl_add_u64 v[4:5], v[4:5], 0, s[4:5]
	s_mov_b32 s18, 0
	v_mov_b32_e32 v8, 0
	v_mov_b32_e32 v9, v3
	v_mov_b32_e32 v6, 0
	v_mov_b32_e32 v7, v3
	s_waitcnt vmcnt(0)
.LBB0_1475:
	v_add_co_u32_e32 v12, vcc, 0xffc80000, v4
	v_readlane_b32 s20, v11, s18
	v_addc_co_u32_e32 v13, vcc, -1, v5, vcc
	v_add_co_u32_e32 v16, vcc, 0xffd00000, v4
	global_load_dwordx2 v[14:15], v[12:13], off
	s_nop 0
	v_addc_co_u32_e32 v17, vcc, -1, v5, vcc
	v_add_co_u32_e32 v20, vcc, 0xffd80000, v4
	global_load_dwordx2 v[18:19], v[16:17], off
	s_nop 0
	v_addc_co_u32_e32 v21, vcc, -1, v5, vcc
	v_add_co_u32_e32 v24, vcc, 0xffe00000, v4
	global_load_dwordx2 v[22:23], v[20:21], off
	s_nop 0
	v_addc_co_u32_e32 v25, vcc, -1, v5, vcc
	v_add_co_u32_e32 v28, vcc, 0xffe80000, v4
	global_load_dwordx2 v[26:27], v[24:25], off
	s_nop 0
	v_addc_co_u32_e32 v29, vcc, -1, v5, vcc
	v_add_co_u32_e32 v30, vcc, 0xfff00000, v4
	s_add_i32 s4, s18, 1
	s_nop 0
	v_addc_co_u32_e32 v31, vcc, -1, v5, vcc
	global_load_dwordx2 v[32:33], v[28:29], off
	global_load_dwordx2 v[34:35], v[30:31], off
	v_add_co_u32_e32 v36, vcc, 0xfff80000, v4
	s_add_i32 s21, s18, 6
	s_nop 0
	v_addc_co_u32_e32 v37, vcc, -1, v5, vcc
	global_load_dwordx2 v[38:39], v[36:37], off
	global_load_dwordx2 v[40:41], v[4:5], off
	v_cvt_pk_bf16_f32 v42, v8, v7
	v_cvt_pk_bf16_f32 v43, v6, v9
	global_store_dwordx2 v[12:13], v[42:43], off
	s_add_i32 s8, s18, 2
	s_add_i32 s23, s18, 7
	v_readlane_b32 s22, v11, s4
	s_add_i32 s10, s18, 3
	v_readlane_b32 s16, v11, s8
	s_add_i32 s12, s18, 4
	v_readlane_b32 s14, v11, s10
	v_readlane_b32 s12, v11, s12
	s_add_i32 s19, s18, 5
	v_readlane_b32 s10, v11, s19
	v_readlane_b32 s8, v11, s21
	v_readlane_b32 s4, v11, s23
	s_waitcnt vmcnt(8)
	v_lshlrev_b32_e32 v13, 16, v15
	v_and_b32_e32 v43, s0, v15
	v_and_b32_e32 v42, 0xffff0000, v14
	v_lshlrev_b32_e32 v14, 16, v14
	v_and_b32_e32 v15, 0xffff0000, v15
	v_pk_mov_b32 v[12:13], v[12:13], v[42:43] op_sel:[1,0]
	s_waitcnt vmcnt(7)
	v_lshlrev_b32_e32 v43, 16, v19
	v_and_b32_e32 v45, s0, v19
	v_and_b32_e32 v44, 0xffff0000, v18
	v_pk_fma_f32 v[8:9], v[8:9], s[20:21], v[14:15] op_sel_hi:[1,0,1]
	v_lshlrev_b32_e32 v14, 16, v18
	v_and_b32_e32 v15, 0xffff0000, v19
	v_pk_fma_f32 v[6:7], v[6:7], s[20:21], v[12:13] op_sel_hi:[1,0,1]
	v_pk_mov_b32 v[12:13], v[42:43], v[44:45] op_sel:[1,0]
	s_waitcnt vmcnt(6)
	v_and_b32_e32 v47, 0xffff0000, v22
	v_lshlrev_b32_e32 v46, 16, v23
	v_pk_fma_f32 v[14:15], v[8:9], s[22:23], v[14:15] op_sel_hi:[1,0,1]
	v_pk_fma_f32 v[12:13], v[6:7], s[22:23], v[12:13] op_sel_hi:[1,0,1]
	v_cvt_pk_bf16_f32 v8, v8, v7
	v_cvt_pk_bf16_f32 v9, v6, v9
	global_store_dwordx2 v[16:17], v[8:9], off
	v_cvt_pk_bf16_f32 v6, v14, v13
	v_cvt_pk_bf16_f32 v7, v12, v15
	v_lshlrev_b32_e32 v18, 16, v22
	v_and_b32_e32 v19, 0xffff0000, v23
	global_store_dwordx2 v[20:21], v[6:7], off
	s_waitcnt vmcnt(7)
	v_and_b32_e32 v7, 0xffff0000, v26
	v_lshlrev_b32_e32 v6, 16, v27
	v_pk_fma_f32 v[8:9], v[12:13], s[16:17], v[46:47] op_sel_hi:[1,0,1]
	v_lshlrev_b32_e32 v22, 16, v26
	v_and_b32_e32 v23, 0xffff0000, v27
	v_pk_fma_f32 v[12:13], v[8:9], s[14:15], v[6:7] op_sel_hi:[1,0,1]
	s_waitcnt vmcnt(6)
	v_lshlrev_b32_e32 v7, 16, v33
	v_and_b32_e32 v6, 0xffff0000, v32
	v_pk_fma_f32 v[14:15], v[14:15], s[16:17], v[18:19] op_sel_hi:[1,0,1]
	v_pk_fma_f32 v[16:17], v[12:13], s[12:13], v[6:7] op_sel:[0,0,1] op_sel_hi:[1,0,0]
	v_cvt_pk_bf16_f32 v18, v14, v9
	v_cvt_pk_bf16_f32 v19, v8, v15
	global_store_dwordx2 v[24:25], v[18:19], off
	v_pk_fma_f32 v[8:9], v[14:15], s[14:15], v[22:23] op_sel_hi:[1,0,1]
	s_waitcnt vmcnt(6)
	v_lshlrev_b32_e32 v7, 16, v35
	v_cvt_pk_bf16_f32 v14, v8, v13
	v_cvt_pk_bf16_f32 v15, v12, v9
	v_lshlrev_b32_e32 v12, 16, v32
	v_and_b32_e32 v13, 0xffff0000, v33
	global_store_dwordx2 v[28:29], v[14:15], off
	v_pk_fma_f32 v[8:9], v[8:9], s[12:13], v[12:13] op_sel_hi:[1,0,1]
	v_and_b32_e32 v6, 0xffff0000, v34
	v_cvt_pk_bf16_f32 v12, v8, v17
	v_cvt_pk_bf16_f32 v13, v16, v9
	global_store_dwordx2 v[30:31], v[12:13], off
	v_lshlrev_b32_e32 v12, 16, v34
	v_and_b32_e32 v13, 0xffff0000, v35
	v_pk_fma_f32 v[20:21], v[16:17], s[10:11], v[6:7] op_sel:[0,0,1] op_sel_hi:[1,0,0]
	v_pk_fma_f32 v[8:9], v[8:9], s[10:11], v[12:13] op_sel_hi:[1,0,1]
	s_waitcnt vmcnt(7)
	v_lshlrev_b32_e32 v7, 16, v39
	v_cvt_pk_bf16_f32 v12, v8, v21
	v_cvt_pk_bf16_f32 v13, v20, v9
	v_and_b32_e32 v6, 0xffff0000, v38
	global_store_dwordx2 v[36:37], v[12:13], off
	v_lshlrev_b32_e32 v12, 16, v38
	v_and_b32_e32 v13, 0xffff0000, v39
	v_pk_fma_f32 v[26:27], v[20:21], s[8:9], v[6:7] op_sel:[0,0,1] op_sel_hi:[1,0,0]
	v_pk_fma_f32 v[8:9], v[8:9], s[8:9], v[12:13] op_sel_hi:[1,0,1]
	s_waitcnt vmcnt(7)
	v_lshlrev_b32_e32 v7, 16, v41
	v_cvt_pk_bf16_f32 v12, v8, v27
	v_cvt_pk_bf16_f32 v13, v26, v9
	v_and_b32_e32 v6, 0xffff0000, v40
	global_store_dwordx2 v[4:5], v[12:13], off
	v_lshlrev_b32_e32 v12, 16, v40
	v_and_b32_e32 v13, 0xffff0000, v41
	v_pk_fma_f32 v[6:7], v[26:27], s[4:5], v[6:7] op_sel:[0,0,1] op_sel_hi:[1,0,0]
	v_pk_fma_f32 v[8:9], v[8:9], s[4:5], v[12:13] op_sel_hi:[1,0,1]
	s_add_i32 s4, s18, 8
	v_lshl_add_u64 v[4:5], v[4:5], 0, s[6:7]
	s_cmp_lt_u32 s18, 56
	s_mov_b32 s18, s4
	s_cbranch_scc1 .LBB0_1475
	s_add_i32 s17, s17, s75
	s_add_i32 s13, s13, s15
	s_cmpk_lt_i32 s17, 0x100
	s_cbranch_scc1 .LBB0_1474
